# sibling barrier: the L1 invalidate (buffer_inv sc1) is issued with the arrival atomic, under the wait for the siblings, instead of after the match (all waves of the workgroup are parked and have no lo
# baseline (speedup 1.0000x reference)
.LBB0_78:
	s_or_b64 exec, exec, s[4:5]
	s_getreg_b32 s8, hwreg(HW_REG_XCC_ID, 0, 4)
	s_waitcnt vmcnt(0)
	s_barrier
	s_mov_b64 s[4:5], exec
	v_readlane_b32 s6, v253, 9
	v_readlane_b32 s7, v253, 10
	s_and_b64 s[6:7], s[4:5], s[6:7]
	s_mov_b64 exec, s[6:7]
	s_cbranch_execz .LBB0_108
	v_readlane_b32 s9, v254, 57
	s_cmp_eq_u32 s9, 0
	s_cbranch_scc1 .Llb_grid_b1
	v_readlane_b32 s8, v253, 43
	v_readlane_b32 s9, v253, 44
	v_readlane_b32 s10, v253, 0
	ds_read_b32 v5, v156 offset:8
	s_and_b32 s10, s10, 63
	s_lshl_b32 s10, s10, 2
	v_mov_b32_e32 v0, s10
	v_mov_b32_e32 v1, 1
	s_waitcnt vmcnt(0) lgkmcnt(0)
	v_readfirstlane_b32 s11, v5
	s_cmp_eq_u32 s11, 0
	s_cbranch_scc1 .Llb_rel_b1
	buffer_wbl2 sc1
	s_waitcnt vmcnt(0)
	global_atomic_add v2, v0, v1, s[8:9] sc0
	s_mov_b32 s11, 0
	s_waitcnt vmcnt(0)
	v_readfirstlane_b32 s12, v2
	s_and_b32 s13, s12, 3
	s_or_b32 s12, s12, 3
	s_add_u32 s12, s12, 1
	s_cmp_eq_u32 s13, 3
	s_cbranch_scc1 .Llb_donex_b1

.Llb_rel_b1:
	buffer_inv sc1
	global_atomic_add v2, v0, v1, s[8:9] sc0
	s_mov_b32 s11, 0
	s_waitcnt vmcnt(0)
	v_readfirstlane_b32 s12, v2
	s_and_b32 s13, s12, 3
	s_or_b32 s12, s12, 3
	s_add_u32 s12, s12, 1
	s_cmp_eq_u32 s13, 3
	s_cbranch_scc1 .Llb_done_b1

.Llb_done_b1:
	s_branch .LBB0_108

.Lconv_ret1:
	s_getreg_b32 s8, hwreg(HW_REG_XCC_ID, 0, 4)
	s_waitcnt vmcnt(0)
	s_waitcnt vmcnt(0)
	s_barrier
	s_mov_b64 s[4:5], exec
	v_readlane_b32 s6, v253, 9
	v_readlane_b32 s7, v253, 10
	s_and_b64 s[6:7], s[4:5], s[6:7]
	s_mov_b64 exec, s[6:7]
	s_cbranch_execz .LBB0_147
	v_readlane_b32 s8, v253, 43
	v_readlane_b32 s9, v253, 44
	v_readlane_b32 s10, v253, 0
	ds_read_b32 v5, v156 offset:8
	s_and_b32 s10, s10, 63
	s_lshl_b32 s10, s10, 2
	v_mov_b32_e32 v0, s10
	v_mov_b32_e32 v1, 1
	s_waitcnt vmcnt(0) lgkmcnt(0)
	v_readfirstlane_b32 s11, v5
	s_cmp_eq_u32 s11, 0
	s_cbranch_scc1 .Llb_rel_b2
	buffer_wbl2 sc1
	s_waitcnt vmcnt(0)
	global_atomic_add v2, v0, v1, s[8:9] sc0
	s_mov_b32 s11, 0
	s_waitcnt vmcnt(0)
	v_readfirstlane_b32 s12, v2
	s_and_b32 s13, s12, 3
	s_or_b32 s12, s12, 3
	s_add_u32 s12, s12, 1
	s_cmp_eq_u32 s13, 3
	s_cbranch_scc1 .Llb_donex_b2

.LBB0_156:
	s_getreg_b32 s6, hwreg(HW_REG_XCC_ID, 0, 4)
	s_waitcnt vmcnt(0)
	s_barrier
	s_mov_b64 s[0:1], exec
	v_readlane_b32 s4, v253, 9
	v_readlane_b32 s5, v253, 10
	s_and_b64 s[4:5], s[0:1], s[4:5]
	s_mov_b64 exec, s[4:5]
	s_cbranch_execz .LBB0_186
	v_readlane_b32 s8, v253, 43
	v_readlane_b32 s9, v253, 44
	v_readlane_b32 s10, v253, 0
	ds_read_b32 v5, v156 offset:8
	s_and_b32 s10, s10, 63
	s_lshl_b32 s10, s10, 2
	v_mov_b32_e32 v0, s10
	v_mov_b32_e32 v1, 1
	s_waitcnt vmcnt(0) lgkmcnt(0)
	v_readfirstlane_b32 s11, v5
	s_cmp_eq_u32 s11, 0
	s_cbranch_scc1 .Llb_rel_b3
	buffer_wbl2 sc1
	s_waitcnt vmcnt(0)
	global_atomic_add v2, v0, v1, s[8:9] sc0
	s_mov_b32 s11, 0
	s_waitcnt vmcnt(0)
	v_readfirstlane_b32 s12, v2
	s_and_b32 s13, s12, 3
	s_or_b32 s12, s12, 3
	s_add_u32 s12, s12, 1
	s_cmp_eq_u32 s13, 3
	s_cbranch_scc1 .Llb_donex_b3

.LBB0_189:
	s_or_b64 exec, exec, s[0:1]
	s_getreg_b32 s6, hwreg(HW_REG_XCC_ID, 0, 4)
	s_waitcnt vmcnt(0)
	s_barrier
	s_mov_b64 s[0:1], exec
	v_readlane_b32 s4, v253, 9
	v_readlane_b32 s5, v253, 10
	s_and_b64 s[4:5], s[0:1], s[4:5]
	s_mov_b64 exec, s[4:5]
	s_cbranch_execz .LBB0_219
	v_readlane_b32 s8, v253, 43
	v_readlane_b32 s9, v253, 44
	v_readlane_b32 s10, v253, 0
	ds_read_b32 v5, v156 offset:8
	s_and_b32 s10, s10, 63
	s_lshl_b32 s10, s10, 2
	v_mov_b32_e32 v0, s10
	v_mov_b32_e32 v1, 1
	s_waitcnt vmcnt(0) lgkmcnt(0)
	v_readfirstlane_b32 s11, v5
	s_cmp_eq_u32 s11, 0
	s_cbranch_scc1 .Llb_rel_b4
	buffer_wbl2 sc1
	s_waitcnt vmcnt(0)
	global_atomic_add v2, v0, v1, s[8:9] sc0
	s_mov_b32 s11, 0
	s_waitcnt vmcnt(0)
	v_readfirstlane_b32 s12, v2
	s_and_b32 s13, s12, 3
	s_or_b32 s12, s12, 3
	s_add_u32 s12, s12, 1
	s_cmp_eq_u32 s13, 3
	s_cbranch_scc1 .Llb_donex_b4

.Lconv_ret3:
	s_getreg_b32 s6, hwreg(HW_REG_XCC_ID, 0, 4)
	s_waitcnt vmcnt(0)
	s_waitcnt vmcnt(0)
	s_barrier
	s_mov_b64 s[0:1], exec
	v_readlane_b32 s4, v253, 9
	v_readlane_b32 s5, v253, 10
	s_and_b64 s[4:5], s[0:1], s[4:5]
	s_mov_b64 exec, s[4:5]
	s_cbranch_execz .LBB0_696
	v_readlane_b32 s8, v253, 43
	v_readlane_b32 s9, v253, 44
	v_readlane_b32 s10, v253, 0
	ds_read_b32 v5, v156 offset:8
	s_and_b32 s10, s10, 63
	s_lshl_b32 s10, s10, 2
	v_mov_b32_e32 v0, s10
	v_mov_b32_e32 v1, 1
	s_waitcnt vmcnt(0) lgkmcnt(0)
	v_readfirstlane_b32 s11, v5
	s_cmp_eq_u32 s11, 0
	s_cbranch_scc1 .Llb_rel_b12
	buffer_wbl2 sc1
	s_waitcnt vmcnt(0)
	global_atomic_add v2, v0, v1, s[8:9] sc0
	s_mov_b32 s11, 0
	s_waitcnt vmcnt(0)
	v_readfirstlane_b32 s12, v2
	s_and_b32 s13, s12, 3
	s_or_b32 s12, s12, 3
	s_add_u32 s12, s12, 1
	s_cmp_eq_u32 s13, 3
	s_cbranch_scc1 .Llb_donex_b12

.LBB0_706:
	v_readlane_b32 s8, v253, 43
	v_readlane_b32 s9, v253, 44
	v_readlane_b32 s10, v253, 0
	ds_read_b32 v5, v156 offset:8
	s_and_b32 s10, s10, 63
	s_lshl_b32 s10, s10, 2
	v_mov_b32_e32 v0, s10
	v_mov_b32_e32 v1, 1
	s_waitcnt vmcnt(0) lgkmcnt(0)
	v_readfirstlane_b32 s11, v5
	s_cmp_eq_u32 s11, 0
	s_cbranch_scc1 .Llb_rel_b13
	buffer_wbl2 sc1
	s_waitcnt vmcnt(0)
	global_atomic_add v2, v0, v1, s[8:9] sc0
	s_mov_b32 s11, 0
	s_waitcnt vmcnt(0)
	v_readfirstlane_b32 s12, v2
	s_and_b32 s13, s12, 3
	s_or_b32 s12, s12, 3
	s_add_u32 s12, s12, 1
	s_cmp_eq_u32 s13, 3
	s_cbranch_scc1 .Llb_donex_b13

.Llb_done_b13:
	s_branch .Llb_to74
	v_readlane_b32 s4, v253, 43
	s_lshl_b32 s6, s6, 8
	v_readlane_b32 s5, v253, 44
	s_and_b32 s6, s6, 0xf00
	s_add_u32 s13, s4, s6
	s_addc_u32 s12, s5, 0
	v_mov_b32_e32 v0, s13
	v_add_co_u32_e32 v2, vcc, 0x1000, v0
	v_mov_b32_e32 v0, s12
	s_nop 0
	v_addc_co_u32_e32 v3, vcc, 0, v0, vcc
	s_waitcnt vmcnt(0) expcnt(0) lgkmcnt(0)
	ds_read_b32 v4, v156
	ds_read_b32 v1, v157
	flat_atomic_add v2, v[2:3], v158 offset:1024 sc0
	s_waitcnt lgkmcnt(0)
	v_cvt_f32_u32_e32 v0, v4
	v_sub_u32_e32 v3, 0, v4
	v_rcp_iflag_f32_e32 v0, v0
	s_nop 0
	v_mul_f32_e32 v0, 0x4f7ffffe, v0
	v_cvt_u32_f32_e32 v0, v0
	v_mul_lo_u32 v3, v3, v0
	v_mul_hi_u32 v3, v0, v3
	v_add_u32_e32 v0, v0, v3
	s_waitcnt vmcnt(0)
	v_mul_hi_u32 v0, v2, v0
	v_mul_lo_u32 v3, v0, v4
	v_sub_u32_e32 v3, v2, v3
	v_add_u32_e32 v5, 1, v0
	v_cmp_ge_u32_e32 vcc, v3, v4
	v_add_u32_e32 v2, 1, v2
	s_nop 0
	v_cndmask_b32_e32 v0, v0, v5, vcc
	v_sub_u32_e32 v5, v3, v4
	v_cndmask_b32_e32 v3, v3, v5, vcc
	v_add_u32_e32 v5, 1, v0
	v_cmp_ge_u32_e32 vcc, v3, v4
	s_nop 1
	v_cndmask_b32_e32 v0, v0, v5, vcc
	v_mul_lo_u32 v3, v4, v0
	v_add_u32_e32 v3, v3, v4
	v_cmp_ne_u32_e32 vcc, v2, v3
	s_and_saveexec_b64 s[6:7], vcc
	s_xor_b64 s[6:7], exec, s[6:7]
	s_cbranch_execz .LBB0_719
	v_mov_b32_e32 v1, s13
	v_add_co_u32_e32 v2, vcc, 0x2000, v1
	v_mov_b32_e32 v1, s12
	s_nop 0
	v_addc_co_u32_e32 v3, vcc, 0, v1, vcc
	flat_load_dword v1, v[2:3] offset:1024 sc1
	s_add_u32 s10, s13, 0x2400
	s_addc_u32 s11, s12, 0
	s_waitcnt vmcnt(0) lgkmcnt(0)
	v_cmp_eq_u32_e32 vcc, v1, v0
	s_and_saveexec_b64 s[8:9], vcc
	s_cbranch_execz .LBB0_718
	s_mov_b32 s21, 1
	s_mov_b64 s[14:15], 0
	s_branch .LBB0_710
